# scan Y stage: all state/G fragment LDS reads issued together right after barrier 2 with counted waits, C*S chain back-to-back
# baseline (speedup 1.0000x reference)
; #define LAS __attribute__((address_space(3)))
; __device__ __forceinline__ unsigned pk2(float lo, float hi) { unsigned r; asm volatile("v_cvt_pk_bf16_f32 %0, %1, %2" : "=v"(r) : "v"(lo), "v"(hi)); return r; }
; __device__ __forceinline__ float bf_lo(unsigned w) { return __uint_as_float(w << 16); }
; __device__ __forceinline__ float bf_hi(unsigned w) { return __uint_as_float(w & 0xffff0000u); }
; __device__ __forceinline__ float silu_f(float x) { return x * __builtin_amdgcn_rcpf(1.0f + __expf(-x)); }
; template <bool DRY>
; __device__ __forceinline__ void ssd_chunk(SsdRegs& R, f32x4 (&st)[2], LAS unsigned char* L, bf16_t* BIG, const float* DT, float* SSQY, const SsdItem& I, int c, int tid, int lane, int wave, int li, int pi, int c16, int q4) {
;     ...
;     const bf16x8 xy0 = pi ? xfr[1][0] : xfr[0][0], xy1 = pi ? xfr[1][1] : xfr[0][1];
;     st[0] = stn[0]; st[1] = stn[1];
;     __syncthreads();
;     {
;         f32x4 d1 = (f32x4){0.f, 0.f, 0.f, 0.f}, d2 = (f32x4){0.f, 0.f, 0.f, 0.f};
; #pragma unroll
;         for (int kk = 0; kk < 2; ++kk) d1 = __builtin_amdgcn_mfma_f32_16x16x32_bf16(kk ? xy1 : xy0, SSD_FRAG(GG, PT, 16 * li, kk), d1, 0, 0, 0);
; #pragma unroll
;         for (int kk = 0; kk < 4; ++kk) d2 = __builtin_amdgcn_mfma_f32_16x16x32_bf16(SSD_FRAG(SB, PC, 16 * pi, kk), cfr[kk], d2, 0, 0, 0);
;         const int l = 16 * li + c16; const float ea_l = __expf(*(const LAS float*)(SCW + l * 4));
;         const float zf[4] = {bf_lo(zc.x), bf_hi(zc.x), bf_lo(zc.y), bf_hi(zc.y)};
;         float yg[4], sq = 0.f;
;         const u32x2 xr = *(const LAS u32x2*)(L + XI + l * PX + (16 * pi + 4 * q4) * 2);
;         const float xs[4] = {bf_lo(xr.x), bf_hi(xr.x), bf_lo(xr.y), bf_hi(xr.y)};
; #pragma unroll
;         for (int e = 0; e < 4; ++e) { const float xv = xs[e];
;             const float y = d1[e] + ea_l * d2[e] + I.Dh * xv; yg[e] = y * silu_f(zf[e]); sq += yg[e] * yg[e]; }
;         u32x2 w; w.x = pk2(yg[0], yg[1]); w.y = pk2(yg[2], yg[3]);
;         if (!DRY) *(u32x2*)((char*)BIG + row0 * (BIGW * 2) + I.offZ) = w;
;         sq += __shfl_xor(sq, 16); sq += __shfl_xor(sq, 32);
;         if (DRY) { if (sq == 12345.678f) SSQY[0] = 1.f; } else if (q4 == 0) SSQY[(size_t)(I.h * 4 + I.ph * 2 + pi) * M_ + row0 + l] = sq;
;     }
.LBB0_733:
	v_add_u32_e32 v145, s69, v113
	s_waitcnt lgkmcnt(1)
	ds_write_b64 v145, v[106:107]
	ds_read_b64_tr_b16 v[146:147], v194 offset:17408
	ds_read_b64_tr_b16 v[148:149], v194 offset:18496
	v_exp_f32_e32 v76, s3
	ds_read_b64_tr_b16 v[152:153], v138 offset:35200
	ds_read_b64_tr_b16 v[150:151], v138 offset:34816
	ds_read_b64_tr_b16 v[154:155], v194 offset:26112
	ds_read_b64_tr_b16 v[156:157], v194 offset:27200
	ds_read_b64_tr_b16 v[158:159], v138 offset:37888
	ds_read_b64_tr_b16 v[160:161], v138 offset:38272
	ds_read_b64_tr_b16 v[162:163], v138 offset:34848
	ds_read_b64_tr_b16 v[164:165], v138 offset:35232
	ds_read_b64_tr_b16 v[166:167], v138 offset:37920
	ds_read_b64_tr_b16 v[168:169], v138 offset:38304
	v_pk_mul_f32 v[52:53], v[52:53], v[76:77] op_sel_hi:[1,0]
	v_pk_mul_f32 v[50:51], v[50:51], v[76:77] op_sel_hi:[1,0]
	v_pk_mul_f32 v[56:57], v[56:57], v[76:77] op_sel_hi:[1,0]
	v_pk_mul_f32 v[54:55], v[54:55], v[76:77] op_sel_hi:[1,0]
	s_waitcnt lgkmcnt(8)
	v_mfma_f32_16x16x32_bf16 v[50:53], v[146:149], v[150:153], v[50:53]
	ds_read_b64_tr_b16 v[196:197], v83 offset:53248
	ds_read_b64_tr_b16 v[198:199], v83 offset:53632
	ds_read_b64_tr_b16 v[200:201], v83 offset:56320
	ds_read_b64_tr_b16 v[202:203], v83 offset:56704
	v_add_u32_e32 v143, v112, v111
	s_waitcnt lgkmcnt(0)
	s_barrier
	ds_read_b128 v[220:223], v123
	ds_read_b128 v[224:227], v123 offset:64
	ds_read_b128 v[228:231], v123 offset:128
	ds_read_b128 v[232:235], v123 offset:192
	ds_read_b128 v[150:153], v143
	ds_read_b128 v[236:239], v143 offset:64
	ds_read_b32 v76, v132
	v_mfma_f32_16x16x32_bf16 v[54:57], v[146:149], v[162:165], v[54:57]
	v_mfma_f32_16x16x32_bf16 v[50:53], v[154:157], v[158:161], v[50:53]
	v_mfma_f32_16x16x32_bf16 v[54:57], v[154:157], v[166:169], v[54:57]
	s_waitcnt lgkmcnt(6)
	v_mfma_f32_16x16x32_bf16 v[70:73], v[220:223], v[70:73], 0
	s_waitcnt lgkmcnt(5)
	v_mfma_f32_16x16x32_bf16 v[66:69], v[224:227], v[66:69], v[70:73]
	s_waitcnt lgkmcnt(4)
	v_mfma_f32_16x16x32_bf16 v[62:65], v[228:231], v[62:65], v[66:69]
	s_waitcnt lgkmcnt(3)
	v_mfma_f32_16x16x32_bf16 v[58:61], v[232:235], v[58:61], v[62:65]
	s_waitcnt lgkmcnt(2)
	v_mfma_f32_16x16x32_bf16 v[146:149], v[196:199], v[150:153], 0
	v_lshlrev_b32_e32 v70, 16, v96
	s_waitcnt lgkmcnt(0)
	v_exp_f32_e32 v72, v76
	v_mul_f32_e32 v62, 0xbfb8aa3b, v70
	v_exp_f32_e32 v71, v62
	v_mfma_f32_16x16x32_bf16 v[62:65], v[200:203], v[236:239], v[146:149]
	ds_read_b64 v[66:67], v139 offset:53248
	s_nop 6
	v_fma_f32 v62, v58, v72, v62
	v_add_f32_e32 v58, 1.0, v71
	v_rcp_f32_e32 v76, v58
	v_and_b32_e32 v58, 0xffff0000, v96
	v_mul_f32_e32 v68, 0xbfb8aa3b, v58
	v_exp_f32_e32 v73, v68
	s_waitcnt lgkmcnt(0)
	v_lshlrev_b32_e32 v71, 16, v66
	v_pk_mul_f32 v[68:69], v[76:77], v[70:71]
	v_fma_f32 v63, v59, v72, v63
	v_add_f32_e32 v62, v62, v69
	v_add_f32_e32 v69, 1.0, v73
	v_rcp_f32_e32 v76, v69
	v_and_b32_e32 v59, 0xffff0000, v66
	v_mul_f32_e32 v62, v68, v62
	v_fma_f32 v64, v60, v72, v64
	v_pk_mul_f32 v[58:59], v[76:77], v[58:59]
	v_fmac_f32_e32 v65, v61, v72
	v_add_f32_e32 v59, v63, v59
	v_mul_f32_e32 v63, v58, v59
	v_lshlrev_b32_e32 v58, 16, v97
	v_mul_f32_e32 v59, 0xbfb8aa3b, v58
	v_exp_f32_e32 v68, v59
	v_lshlrev_b32_e32 v59, 16, v67
	v_and_b32_e32 v61, 0xffff0000, v67
	v_mul_f32_e32 v66, v63, v63
	v_add_f32_e32 v60, 1.0, v68
	v_rcp_f32_e32 v76, v60
	v_and_b32_e32 v60, 0xffff0000, v97
	v_mul_f32_e32 v68, 0xbfb8aa3b, v60
	v_exp_f32_e32 v68, v68
	v_pk_mul_f32 v[58:59], v[76:77], v[58:59]
	v_fmac_f32_e32 v66, v62, v62
	v_add_f32_e32 v59, v64, v59
	v_mul_f32_e32 v64, v58, v59
	v_add_f32_e32 v58, 1.0, v68
	v_rcp_f32_e32 v76, v58
	v_fmac_f32_e32 v66, v64, v64
	v_pk_mul_f32 v[58:59], v[76:77], v[60:61]
	s_nop 0
	v_add_f32_e32 v59, v65, v59
	v_mul_f32_e32 v58, v58, v59
	v_fmac_f32_e32 v66, v58, v58
	v_mov_b32_e32 v59, v66
	v_cvt_pk_bf16_f32 v60, v62, v63
	v_cvt_pk_bf16_f32 v61, v64, v58
	v_permlane16_swap_b32 v59, v66
	global_store_dwordx2 v[78:79], v[60:61], off
	v_add_f32_e32 v58, v66, v59
	v_mov_b32_e32 v59, v58
	s_mov_b64 s[0:1], 0xc0000
	v_lshl_add_u64 v[78:79], v[78:79], 0, s[0:1]
	s_nop 0
	v_permlane32_swap_b32 v59, v58
	s_and_saveexec_b64 s[0:1], s[18:19]
	s_cbranch_execz .LBB0_735
	v_add_f32_e32 v60, v58, v59
	global_store_dword v[90:91], v60, off

; #define LAS __attribute__((address_space(3)))
; __device__ __forceinline__ unsigned pk2(float lo, float hi) { unsigned r; asm volatile("v_cvt_pk_bf16_f32 %0, %1, %2" : "=v"(r) : "v"(lo), "v"(hi)); return r; }
; __device__ __forceinline__ float bf_lo(unsigned w) { return __uint_as_float(w << 16); }
; __device__ __forceinline__ float bf_hi(unsigned w) { return __uint_as_float(w & 0xffff0000u); }
; __device__ __forceinline__ float silu_f(float x) { return x * __builtin_amdgcn_rcpf(1.0f + __expf(-x)); }
; template <bool DRY>
; __device__ __forceinline__ void ssd_chunk(SsdRegs& R, f32x4 (&st)[2], LAS unsigned char* L, bf16_t* BIG, const float* DT, float* SSQY, const SsdItem& I, int c, int tid, int lane, int wave, int li, int pi, int c16, int q4) {
;     ...
;     const bf16x8 xy0 = pi ? xfr[1][0] : xfr[0][0], xy1 = pi ? xfr[1][1] : xfr[0][1];
;     st[0] = stn[0]; st[1] = stn[1];
;     __syncthreads();
;     {
;         f32x4 d1 = (f32x4){0.f, 0.f, 0.f, 0.f}, d2 = (f32x4){0.f, 0.f, 0.f, 0.f};
; #pragma unroll
;         for (int kk = 0; kk < 2; ++kk) d1 = __builtin_amdgcn_mfma_f32_16x16x32_bf16(kk ? xy1 : xy0, SSD_FRAG(GG, PT, 16 * li, kk), d1, 0, 0, 0);
; #pragma unroll
;         for (int kk = 0; kk < 4; ++kk) d2 = __builtin_amdgcn_mfma_f32_16x16x32_bf16(SSD_FRAG(SB, PC, 16 * pi, kk), cfr[kk], d2, 0, 0, 0);
;         const int l = 16 * li + c16; const float ea_l = __expf(*(const LAS float*)(SCW + l * 4));
;         const float zf[4] = {bf_lo(zc.x), bf_hi(zc.x), bf_lo(zc.y), bf_hi(zc.y)};
;         float yg[4], sq = 0.f;
;         const u32x2 xr = *(const LAS u32x2*)(L + XI + l * PX + (16 * pi + 4 * q4) * 2);
;         const float xs[4] = {bf_lo(xr.x), bf_hi(xr.x), bf_lo(xr.y), bf_hi(xr.y)};
; #pragma unroll
;         for (int e = 0; e < 4; ++e) { const float xv = xs[e];
;             const float y = d1[e] + ea_l * d2[e] + I.Dh * xv; yg[e] = y * silu_f(zf[e]); sq += yg[e] * yg[e]; }
;         u32x2 w; w.x = pk2(yg[0], yg[1]); w.y = pk2(yg[2], yg[3]);
;         if (!DRY) *(u32x2*)((char*)BIG + row0 * (BIGW * 2) + I.offZ) = w;
;         sq += __shfl_xor(sq, 16); sq += __shfl_xor(sq, 32);
;         if (DRY) { if (sq == 12345.678f) SSQY[0] = 1.f; } else if (q4 == 0) SSQY[(size_t)(I.h * 4 + I.ph * 2 + pi) * M_ + row0 + l] = sq;
;     }
.LBB0_746:
	s_waitcnt lgkmcnt(1)
	v_exp_f32_e32 v76, s3
	ds_write_b64 v145, v[100:101]
	ds_read_b64_tr_b16 v[100:101], v194 offset:17408
	ds_read_b64_tr_b16 v[102:103], v194 offset:18496
	ds_read_b64_tr_b16 v[150:151], v138 offset:35200
	ds_read_b64_tr_b16 v[148:149], v138 offset:34816
	ds_read_b64_tr_b16 v[152:153], v194 offset:26112
	ds_read_b64_tr_b16 v[154:155], v194 offset:27200
	ds_read_b64_tr_b16 v[156:157], v138 offset:37888
	ds_read_b64_tr_b16 v[158:159], v138 offset:38272
	ds_read_b64_tr_b16 v[162:163], v138 offset:35232
	ds_read_b64_tr_b16 v[160:161], v138 offset:34848
	ds_read_b64_tr_b16 v[166:167], v138 offset:38304
	v_pk_mul_f32 v[52:53], v[52:53], v[76:77] op_sel_hi:[1,0]
	v_pk_mul_f32 v[50:51], v[50:51], v[76:77] op_sel_hi:[1,0]
	ds_read_b64_tr_b16 v[164:165], v138 offset:37920
	v_pk_mul_f32 v[56:57], v[56:57], v[76:77] op_sel_hi:[1,0]
	v_pk_mul_f32 v[54:55], v[54:55], v[76:77] op_sel_hi:[1,0]
	s_waitcnt lgkmcnt(8)
	v_mfma_f32_16x16x32_bf16 v[50:53], v[100:103], v[148:151], v[50:53]
	ds_read_b64_tr_b16 v[196:197], v83 offset:59392
	ds_read_b64_tr_b16 v[198:199], v83 offset:59776
	ds_read_b64_tr_b16 v[200:201], v83 offset:62464
	ds_read_b64_tr_b16 v[202:203], v83 offset:62848
	s_waitcnt lgkmcnt(0)
	s_barrier
	ds_read_b128 v[220:223], v125
	ds_read_b128 v[224:227], v125 offset:64
	ds_read_b128 v[228:231], v125 offset:128
	ds_read_b128 v[232:235], v125 offset:192
	ds_read_b128 v[148:151], v143
	ds_read_b128 v[236:239], v143 offset:64
	ds_read_b32 v76, v132
	v_mfma_f32_16x16x32_bf16 v[54:57], v[100:103], v[160:163], v[54:57]
	v_mfma_f32_16x16x32_bf16 v[50:53], v[152:155], v[156:159], v[50:53]
	v_mfma_f32_16x16x32_bf16 v[54:57], v[152:155], v[164:167], v[54:57]
	s_waitcnt lgkmcnt(6)
	v_mfma_f32_16x16x32_bf16 v[70:73], v[220:223], v[70:73], 0
	s_waitcnt lgkmcnt(5)
	v_mfma_f32_16x16x32_bf16 v[66:69], v[224:227], v[66:69], v[70:73]
	s_waitcnt lgkmcnt(4)
	v_mfma_f32_16x16x32_bf16 v[62:65], v[228:231], v[62:65], v[66:69]
	s_waitcnt lgkmcnt(3)
	v_mfma_f32_16x16x32_bf16 v[58:61], v[232:235], v[58:61], v[62:65]
	s_waitcnt lgkmcnt(2)
	v_mfma_f32_16x16x32_bf16 v[100:103], v[196:199], v[148:151], 0
	v_lshlrev_b32_e32 v68, 16, v92
	v_mul_f32_e32 v69, 0xbfb8aa3b, v68
	v_exp_f32_e32 v69, v69
	s_waitcnt lgkmcnt(0)
	v_exp_f32_e32 v70, v76
	v_mfma_f32_16x16x32_bf16 v[62:65], v[200:203], v[236:239], v[100:103]
	ds_read_b64 v[66:67], v139 offset:59392
	s_nop 7
	v_fma_f32 v62, v58, v70, v62
	v_add_f32_e32 v58, 1.0, v69
	v_rcp_f32_e32 v76, v58
	v_and_b32_e32 v58, 0xffff0000, v92
	v_mul_f32_e32 v69, 0xbfb8aa3b, v58
	v_exp_f32_e32 v71, v69
	s_waitcnt lgkmcnt(0)
	v_lshlrev_b32_e32 v69, 16, v66
	v_pk_mul_f32 v[68:69], v[76:77], v[68:69]
	v_fma_f32 v63, v59, v70, v63
	v_add_f32_e32 v62, v62, v69
	v_add_f32_e32 v69, 1.0, v71
	v_rcp_f32_e32 v76, v69
	v_and_b32_e32 v59, 0xffff0000, v66
	v_mul_f32_e32 v62, v68, v62
	v_fma_f32 v64, v60, v70, v64
	v_pk_mul_f32 v[58:59], v[76:77], v[58:59]
	v_fmac_f32_e32 v65, v61, v70
	v_add_f32_e32 v59, v63, v59
	v_mul_f32_e32 v63, v58, v59
	v_lshlrev_b32_e32 v58, 16, v93
	v_mul_f32_e32 v59, 0xbfb8aa3b, v58
	v_exp_f32_e32 v68, v59
	v_lshlrev_b32_e32 v59, 16, v67
	v_and_b32_e32 v61, 0xffff0000, v67
	v_mul_f32_e32 v66, v63, v63
	v_add_f32_e32 v60, 1.0, v68
	v_rcp_f32_e32 v76, v60
	v_and_b32_e32 v60, 0xffff0000, v93
	v_mul_f32_e32 v68, 0xbfb8aa3b, v60
	v_exp_f32_e32 v68, v68
	v_pk_mul_f32 v[58:59], v[76:77], v[58:59]
	v_fmac_f32_e32 v66, v62, v62
	v_add_f32_e32 v59, v64, v59
	v_mul_f32_e32 v64, v58, v59
	v_add_f32_e32 v58, 1.0, v68
	v_rcp_f32_e32 v76, v58
	v_fmac_f32_e32 v66, v64, v64
	v_pk_mul_f32 v[58:59], v[76:77], v[60:61]
	s_nop 0
	v_add_f32_e32 v59, v65, v59
	v_mul_f32_e32 v58, v58, v59
	v_fmac_f32_e32 v66, v58, v58
	v_mov_b32_e32 v59, v66
	v_cvt_pk_bf16_f32 v60, v62, v63
	v_cvt_pk_bf16_f32 v61, v64, v58
	v_permlane16_swap_b32 v59, v66
	global_store_dwordx2 v[78:79], v[60:61], off
	v_add_f32_e32 v58, v66, v59
	v_mov_b32_e32 v59, v58
	s_mov_b64 s[0:1], 0xc0000
	v_lshl_add_u64 v[78:79], v[78:79], 0, s[0:1]
	s_nop 0
	v_permlane32_swap_b32 v59, v58
	s_and_saveexec_b64 s[0:1], s[18:19]
	s_cbranch_execz .LBB0_719
	v_add_f32_e32 v60, v58, v59
	global_store_dword v[90:91], v60, off offset:256
	s_branch .LBB0_719
